# v62 + layer-2 out-proj weight transpose moved from layer 0 group-B tail to layer 2 group-B tail (has slack there)
# speedup vs baseline: 1.0061x; 1.0061x over previous
.Ltr5_l2:
	s_mov_b32 s0, s37
	s_mov_b32 s2, s37
	v_mbcnt_lo_u32_b32 v0, -1, 0
	v_mbcnt_hi_u32_b32 v0, -1, v0
	s_ashr_i32 s1, s0, 31
	s_lshl_b64 s[0:1], s[0:1], 3
	s_add_u32 s0, s96, s0
	s_addc_u32 s1, s97, s1
	s_load_dwordx2 s[4:5], s[0:1], 0x60
	s_ashr_i32 s0, s2, 31
	v_readlane_b32 s1, v254, 6
	s_add_u32 s1, s1, s2
	v_readlane_b32 s2, v254, 7
	s_addc_u32 s2, s2, s0
	s_waitcnt vmcnt(46)
	v_lshlrev_b32_e32 v4, 4, v0
	s_add_u32 s0, s1, 0x1000000
	s_waitcnt vmcnt(45)
	v_add_u32_e32 v7, s33, v0
	v_and_b32_e32 v0, 0x1f0, v4
	s_addc_u32 s1, s2, 0
	s_waitcnt lgkmcnt(0)
	v_lshl_add_u64 v[2:3], s[4:5], 0, v[0:1]
	s_mov_b64 s[2:3], 0x2000000
	v_and_b32_e32 v4, 48, v4
	v_ashrrev_i32_e32 v5, 5, v7
	v_lshl_add_u64 v[2:3], v[2:3], 0, s[2:3]
	s_waitcnt vmcnt(44)
	v_mul_u32_u24_e32 v8, 0x81, v4
	s_movk_i32 s2, 0x204
	v_add_u32_e32 v0, 0, v0
	v_ashrrev_i32_e32 v6, 2, v7
	v_mul_lo_u32 v9, v5, s2
	v_lshlrev_b32_e32 v8, 2, v8
	v_and_b32_e32 v7, -4, v7
	v_readlane_b32 s14, v253, 60
	v_add3_u32 v7, 0, v8, v7
	s_lshl_b32 s2, s14, 7
	s_lshl_b32 s3, s18, 7
	v_add_u32_e32 v8, v0, v9
	s_branch .LBB0_1154
